# MLA attention PV: all 8 V-fragment LDS reads issued before the exp block, MFMAs with counted lgkmcnt
# baseline (speedup 1.0000x reference)
;     ...
; #pragma unroll
;         for (int di = 0; di < DV / 16; ++di)
; #pragma unroll
;             for (int s2 = 0; s2 < 2; ++s2) {
;                 const u32x2 v0 = *(const u32x2*)(cV + (di * 16 + fr) * LDV + s2 * 32 + fq * 4), v1 = *(const u32x2*)(cV + (di * 16 + fr) * LDV + s2 * 32 + 16 + fq * 4);
;                 const bf16x8 vf = __builtin_bit_cast(bf16x8, ((u32x4){v0[0], v0[1], v1[0], v1[1]}));
; #pragma unroll
;                 for (int mi = 0; mi < MIA; ++mi) o[mi][di] = __builtin_amdgcn_mfma_f32_16x16x32_bf16(vf, pf[mi][s2], o[mi][di], 0, 0, 0);
;             }
.LBB0_717:
	v_mul_f32_e32 v100, 0xbe16c740, v133
	s_mov_b32 s0, 0x3e16c740
	v_lshl_add_u32 v151, s10, 1, v148
	v_add_u32_e32 v156, 0x3800, v151
	ds_read2_b64 v[186:189], v156 offset1:4
	ds_read2_b64 v[190:193], v156 offset0:8 offset1:12
	v_add_u32_e32 v156, 0x4000, v151
	ds_read2_b64 v[194:197], v156 offset0:32 offset1:36
	ds_read2_b64 v[198:201], v156 offset0:40 offset1:44
	v_add_u32_e32 v156, 0x4800, v151
	ds_read2_b64 v[202:205], v156 offset0:64 offset1:68
	ds_read2_b64 v[206:209], v156 offset0:72 offset1:76
	v_add_u32_e32 v156, 0x5000, v151
	ds_read2_b64 v[210:213], v156 offset0:96 offset1:100
	ds_read2_b64 v[214:217], v156 offset0:104 offset1:108
	v_pk_fma_f32 v[52:53], v[52:53], s[0:1], v[100:101] op_sel_hi:[1,0,0]
	v_pk_fma_f32 v[54:55], v[54:55], s[0:1], v[100:101] op_sel_hi:[1,0,0]
	v_pk_fma_f32 v[40:41], v[40:41], s[0:1], v[100:101] op_sel_hi:[1,0,0]
	v_pk_fma_f32 v[42:43], v[42:43], s[0:1], v[100:101] op_sel_hi:[1,0,0]
	v_pk_fma_f32 v[56:57], v[56:57], s[0:1], v[100:101] op_sel_hi:[1,0,0]
	v_pk_fma_f32 v[58:59], v[58:59], s[0:1], v[100:101] op_sel_hi:[1,0,0]
	v_pk_fma_f32 v[68:69], v[68:69], s[0:1], v[100:101] op_sel_hi:[1,0,0]
	v_pk_fma_f32 v[70:71], v[70:71], s[0:1], v[100:101] op_sel_hi:[1,0,0]
	v_exp_f32_e32 v52, v52
	v_exp_f32_e32 v53, v53
	v_exp_f32_e32 v54, v54
	v_exp_f32_e32 v55, v55
	v_exp_f32_e32 v40, v40
	v_exp_f32_e32 v41, v41
	v_exp_f32_e32 v42, v42
	v_exp_f32_e32 v43, v43
	v_exp_f32_e32 v56, v56
	v_exp_f32_e32 v57, v57
	v_exp_f32_e32 v58, v58
	v_exp_f32_e32 v59, v59
	v_exp_f32_e32 v68, v68
	v_exp_f32_e32 v69, v69
	v_exp_f32_e32 v70, v70
	v_exp_f32_e32 v71, v71
	v_cvt_pk_bf16_f32 v108, v76, v77
	v_cvt_pk_bf16_f32 v109, v78, v79
	v_cvt_pk_bf16_f32 v110, v72, v73
	v_cvt_pk_bf16_f32 v111, v74, v75
	v_cvt_pk_bf16_f32 v112, v52, v53
	v_cvt_pk_bf16_f32 v113, v54, v55
	v_cvt_pk_bf16_f32 v114, v40, v41
	v_cvt_pk_bf16_f32 v115, v42, v43
	v_pk_add_f32 v[104:105], v[52:53], v[54:55]
	v_pk_add_f32 v[106:107], v[40:41], v[42:43]
	v_pk_add_f32 v[102:103], v[56:57], v[58:59]
	v_pk_add_f32 v[100:101], v[68:69], v[70:71]
	v_pk_add_f32 v[104:105], v[104:105], v[106:107]
	v_pk_add_f32 v[100:101], v[100:101], v[102:103]
	v_pk_add_f32 v[104:105], v[104:105], v[100:101]
	s_nop 0
	v_add_f32_e32 v100, v104, v105
	v_add_f32_e32 v121, v100, v121
	v_cvt_pk_bf16_f32 v104, v84, v85
	v_cvt_pk_bf16_f32 v105, v86, v87
	v_cvt_pk_bf16_f32 v106, v92, v93
	v_cvt_pk_bf16_f32 v107, v94, v95
	v_cvt_pk_bf16_f32 v100, v56, v57
	v_cvt_pk_bf16_f32 v101, v58, v59
	v_cvt_pk_bf16_f32 v102, v68, v69
	v_cvt_pk_bf16_f32 v103, v70, v71
	s_nop 1
	s_waitcnt lgkmcnt(7)
	v_mfma_f32_16x16x32_bf16 v[20:23], v[186:189], v[108:111], v[20:23]
	v_mfma_f32_16x16x32_bf16 v[28:31], v[186:189], v[112:115], v[28:31]
	s_waitcnt lgkmcnt(6)
	v_mfma_f32_16x16x32_bf16 v[20:23], v[190:193], v[104:107], v[20:23]
	v_mfma_f32_16x16x32_bf16 v[28:31], v[190:193], v[100:103], v[28:31]
	s_waitcnt lgkmcnt(5)
	v_mfma_f32_16x16x32_bf16 v[12:15], v[194:197], v[108:111], v[12:15]
	v_mfma_f32_16x16x32_bf16 v[8:11], v[194:197], v[112:115], v[8:11]
	s_waitcnt lgkmcnt(4)
	v_mfma_f32_16x16x32_bf16 v[12:15], v[198:201], v[104:107], v[12:15]
	v_mfma_f32_16x16x32_bf16 v[8:11], v[198:201], v[100:103], v[8:11]
	s_waitcnt lgkmcnt(3)
	v_mfma_f32_16x16x32_bf16 v[4:7], v[202:205], v[108:111], v[4:7]
	v_mfma_f32_16x16x32_bf16 v[0:3], v[202:205], v[112:115], v[0:3]
	s_waitcnt lgkmcnt(2)
	v_mfma_f32_16x16x32_bf16 v[4:7], v[206:209], v[104:107], v[4:7]
	v_mfma_f32_16x16x32_bf16 v[0:3], v[206:209], v[100:103], v[0:3]
	s_waitcnt lgkmcnt(1)
	v_mfma_f32_16x16x32_bf16 v[16:19], v[210:213], v[108:111], v[16:19]
	v_mfma_f32_16x16x32_bf16 v[24:27], v[210:213], v[112:115], v[24:27]
	s_waitcnt lgkmcnt(0)
	v_mfma_f32_16x16x32_bf16 v[16:19], v[214:217], v[104:107], v[16:19]
	v_mfma_f32_16x16x32_bf16 v[24:27], v[214:217], v[100:103], v[24:27]
	v_mov_b64_e32 v[100:101], v[132:133]
